# router weight staging into LDS de-serialised: eight loads in flight per thread instead of load-wait-write per iteration (phases 5 and 13)
# speedup vs baseline: 1.0065x; 1.0028x over previous
.LBB0_637:
	v_ashrrev_i32_e32 v6, 2, v5
	v_ashrrev_i32_e32 v7, 31, v6
	v_and_b32_e32 v10, 12, v1
	v_lshlrev_b64 v[6:7], 6, v[6:7]
	v_lshlrev_b32_e32 v2, 2, v10
	v_lshl_add_u64 v[6:7], s[12:13], 0, v[6:7]
	v_lshl_add_u64 v[6:7], v[6:7], 0, v[2:3]
	global_load_dwordx4 v[200:203], v[6:7], off
	s_mov_b64 s[2:3], 0x2000
	v_lshl_add_u64 v[6:7], v[6:7], 0, s[2:3]
	global_load_dwordx4 v[204:207], v[6:7], off
	v_lshl_add_u64 v[6:7], v[6:7], 0, s[2:3]
	global_load_dwordx4 v[208:211], v[6:7], off
	v_lshl_add_u64 v[6:7], v[6:7], 0, s[2:3]
	global_load_dwordx4 v[212:215], v[6:7], off
	v_lshl_add_u64 v[6:7], v[6:7], 0, s[2:3]
	global_load_dwordx4 v[216:219], v[6:7], off
	v_lshl_add_u64 v[6:7], v[6:7], 0, s[2:3]
	global_load_dwordx4 v[220:223], v[6:7], off
	v_lshl_add_u64 v[6:7], v[6:7], 0, s[2:3]
	global_load_dwordx4 v[224:227], v[6:7], off
	v_lshl_add_u64 v[6:7], v[6:7], 0, s[2:3]
	global_load_dwordx4 v[228:231], v[6:7], off
	v_and_b32_e32 v2, -4, v5
	v_lshlrev_b32_e32 v10, 12, v10
	v_add3_u32 v2, 0, v10, v2
	s_waitcnt vmcnt(7)
	ds_write2st64_b32 v2, v200, v201 offset0:0 offset1:16
	ds_write2st64_b32 v2, v202, v203 offset0:32 offset1:48
	s_waitcnt vmcnt(6)
	ds_write2st64_b32 v2, v204, v205 offset0:2 offset1:18
	ds_write2st64_b32 v2, v206, v207 offset0:34 offset1:50
	s_waitcnt vmcnt(5)
	ds_write2st64_b32 v2, v208, v209 offset0:4 offset1:20
	ds_write2st64_b32 v2, v210, v211 offset0:36 offset1:52
	s_waitcnt vmcnt(4)
	ds_write2st64_b32 v2, v212, v213 offset0:6 offset1:22
	ds_write2st64_b32 v2, v214, v215 offset0:38 offset1:54
	s_waitcnt vmcnt(3)
	ds_write2st64_b32 v2, v216, v217 offset0:8 offset1:24
	ds_write2st64_b32 v2, v218, v219 offset0:40 offset1:56
	s_waitcnt vmcnt(2)
	ds_write2st64_b32 v2, v220, v221 offset0:10 offset1:26
	ds_write2st64_b32 v2, v222, v223 offset0:42 offset1:58
	s_waitcnt vmcnt(1)
	ds_write2st64_b32 v2, v224, v225 offset0:12 offset1:28
	ds_write2st64_b32 v2, v226, v227 offset0:44 offset1:60
	s_waitcnt vmcnt(0)
	ds_write2st64_b32 v2, v228, v229 offset0:14 offset1:30
	ds_write2st64_b32 v2, v230, v231 offset0:46 offset1:62

.LBB0_1226:
	v_ashrrev_i32_e32 v6, 2, v5
	v_ashrrev_i32_e32 v7, 31, v6
	v_and_b32_e32 v10, 12, v1
	v_lshlrev_b64 v[6:7], 6, v[6:7]
	v_lshlrev_b32_e32 v2, 2, v10
	v_lshl_add_u64 v[6:7], s[16:17], 0, v[6:7]
	v_lshl_add_u64 v[6:7], v[6:7], 0, v[2:3]
	v_add_co_u32_e32 v6, vcc, 0x10000, v6
	v_and_b32_e32 v2, -4, v5
	s_nop 0
	v_addc_co_u32_e32 v7, vcc, 0, v7, vcc
	global_load_dwordx4 v[200:203], v[6:7], off
	s_mov_b64 s[4:5], 0x2000
	v_lshl_add_u64 v[6:7], v[6:7], 0, s[4:5]
	global_load_dwordx4 v[204:207], v[6:7], off
	v_lshl_add_u64 v[6:7], v[6:7], 0, s[4:5]
	global_load_dwordx4 v[208:211], v[6:7], off
	v_lshl_add_u64 v[6:7], v[6:7], 0, s[4:5]
	global_load_dwordx4 v[212:215], v[6:7], off
	v_lshl_add_u64 v[6:7], v[6:7], 0, s[4:5]
	global_load_dwordx4 v[216:219], v[6:7], off
	v_lshl_add_u64 v[6:7], v[6:7], 0, s[4:5]
	global_load_dwordx4 v[220:223], v[6:7], off
	v_lshl_add_u64 v[6:7], v[6:7], 0, s[4:5]
	global_load_dwordx4 v[224:227], v[6:7], off
	v_lshl_add_u64 v[6:7], v[6:7], 0, s[4:5]
	global_load_dwordx4 v[228:231], v[6:7], off
	v_lshlrev_b32_e32 v10, 12, v10
	v_add3_u32 v2, 0, v10, v2
	s_waitcnt vmcnt(7)
	ds_write2st64_b32 v2, v200, v201 offset0:0 offset1:16
	ds_write2st64_b32 v2, v202, v203 offset0:32 offset1:48
	s_waitcnt vmcnt(6)
	ds_write2st64_b32 v2, v204, v205 offset0:2 offset1:18
	ds_write2st64_b32 v2, v206, v207 offset0:34 offset1:50
	s_waitcnt vmcnt(5)
	ds_write2st64_b32 v2, v208, v209 offset0:4 offset1:20
	ds_write2st64_b32 v2, v210, v211 offset0:36 offset1:52
	s_waitcnt vmcnt(4)
	ds_write2st64_b32 v2, v212, v213 offset0:6 offset1:22
	ds_write2st64_b32 v2, v214, v215 offset0:38 offset1:54
	s_waitcnt vmcnt(3)
	ds_write2st64_b32 v2, v216, v217 offset0:8 offset1:24
	ds_write2st64_b32 v2, v218, v219 offset0:40 offset1:56
	s_waitcnt vmcnt(2)
	ds_write2st64_b32 v2, v220, v221 offset0:10 offset1:26
	ds_write2st64_b32 v2, v222, v223 offset0:42 offset1:58
	s_waitcnt vmcnt(1)
	ds_write2st64_b32 v2, v224, v225 offset0:12 offset1:28
	ds_write2st64_b32 v2, v226, v227 offset0:44 offset1:60
	s_waitcnt vmcnt(0)
	ds_write2st64_b32 v2, v228, v229 offset0:14 offset1:30
	ds_write2st64_b32 v2, v230, v231 offset0:46 offset1:62
